# MLA inner loop: removed redundant VALU (zero-init movs, K-operand shuffles via ds_read_b64, dedicated ones vector, out-of-line last-tile masking, no canonicalising max), lsum result in spare regs
# speedup vs baseline: 1.0551x; 1.0551x over previous
; DEVINL void partialSM(f32x16& p0, f32x16& p1, float& m_reg, float& mn, float& alpha, int kvalid, int hi) {
;   constexpr float C = MLA_SCALE * 1.4426950408889634f;
;   if (kvalid < 64) {
; #pragma unroll
;     for (int r = 0; r < 16; ++r) { if (crow(r, hi) >= kvalid) p0[r] = -1e30f; if (32 + crow(r, hi) >= kvalid) p1[r] = -1e30f; }
;   }
;   float pmax = p0[0];
; #pragma unroll
;   for (int r = 1; r < 16; ++r) pmax = fmaxf(pmax, p0[r]);
; #pragma unroll
;   for (int r = 0; r < 16; ++r) pmax = fmaxf(pmax, p1[r]);
;   { auto rr = __builtin_amdgcn_permlane32_swap(__float_as_uint(pmax), __float_as_uint(pmax), false, false);
;     pmax = fmaxf(__uint_as_float(rr[0]), __uint_as_float(rr[1])); }
;   if (__builtin_expect(__all(pmax - m_reg <= THR / MLA_SCALE), 1)) { mn = m_reg; alpha = 1.f; }
;   else { mn = fmaxf(m_reg, pmax); alpha = __builtin_amdgcn_exp2f((m_reg - mn) * C); m_reg = mn; }
;   const float mnC = PSHIFT - mn * C;
;   const f32x2 C2 = {C, C}, M2 = {mnC, mnC};
; #pragma unroll
;   for (int r = 0; r < 16; r += 2) { f32x2 v = {p0[r], p0[r + 1]}; v = __builtin_elementwise_fma(v, C2, M2); p0[r] = v[0]; p0[r + 1] = v[1]; }
; #pragma unroll
; template <bool FUSE>
; DEVINL void qkt(f32x16& p0, f32x16& p1, const char* Ks, const i32x8* q8, int r32, int hi, f32x16& e1) {
;   p0 = f32x16{}; p1 = f32x16{};
;   const char* ka = Ks + hi * 1024 + r32 * 16; const char* kb = Ks + 4096 + hi * 512 + r32 * 8;
;   const char* ra = Ks + 6144 + hi * 1024 + r32 * 16; const char* rb = Ks + 6144 + 2048 + hi * 512 + r32 * 8;
;   u32x4 fa[3][2]; u32x2 fb[3][2];
;     ...
;   QK_LD(0, 0);
; #pragma unroll
;   for (int t = 0; t < 3; ++t) {
;     if (t + 1 < 3) QK_LD(t + 1, (t + 1) % 3);
;     const i32x8 a0 = mk6((int)fa[t][0][0], (int)fa[t][0][1], (int)fa[t][0][2], (int)fa[t][0][3], (int)fb[t][0][0], (int)fb[t][0][1]);
;     const i32x8 a1 = mk6((int)fa[t][1][0], (int)fa[t][1][1], (int)fa[t][1][2], (int)fa[t][1][3], (int)fb[t][1][0], (int)fb[t][1][1]);
;     p0 = MFMA6(a0, q8[t], p0);
;     if (FUSE) {
; #pragma unroll
;       for (int r = 0; r < 3; ++r) { const int rr = t * 6 + r; if (rr < 16) e1[rr] = __builtin_amdgcn_exp2f(e1[rr]); }
;     }
;     p1 = MFMA6(a1, q8[t], p1);
;     if (FUSE) {
; #pragma unroll
;       for (int r = 3; r < 6; ++r) { const int rr = t * 6 + r; if (rr < 16) e1[rr] = __builtin_amdgcn_exp2f(e1[rr]); }
;     }
;     SBAR();
;   }
;     ...
; }
.LBB0_559:
	s_or_b64 exec, exec, s[8:9]
	s_mul_i32 s8, s75, 0x208000
	s_add_u32 s14, s58, s8
	v_add_u32_e32 v0, 0x9000, v172
	s_addc_u32 s15, s59, 0
	v_readfirstlane_b32 s9, v0
	v_add_u32_e32 v2, 0xb000, v172
	v_lshl_add_u64 v[140:141], s[14:15], 0, v[138:139]
	s_mov_b32 m0, s9
	v_readfirstlane_b32 s9, v2
	global_load_lds_dwordx4 v[140:141], off
	v_lshl_add_u64 v[0:1], v[140:141], 0, s[48:49]
	s_mov_b32 m0, s9
	v_lshlrev_b32_e32 v170, 9, v48
	global_load_lds_dwordx4 v[0:1], off
	v_and_b32_e32 v0, 0x3fffffc0, v166
	v_lshl_add_u32 v171, v0, 2, s68
	v_add_u32_e32 v0, 0, v170
	v_lshlrev_b32_e32 v176, 3, v167
	v_lshlrev_b32_e32 v175, 4, v167
	v_add_u32_e32 v49, v0, v176
	v_add3_u32 v173, v0, v170, v175
	v_add_u32_e32 v0, 0x1000, v49
	s_waitcnt vmcnt(0)
	s_waitcnt vmcnt(0) lgkmcnt(0)
	s_barrier
	ds_read2_b64 v[4:7], v0 offset1:32
	ds_read_b128 v[50:53], v173 offset:2048
	ds_read_b128 v[56:59], v173 offset:2560
	ds_read2_b64 v[60:63], v0 offset0:128 offset1:160
	ds_read_b128 v[16:19], v173 offset:512
	ds_read_b128 v[0:3], v173
	s_waitcnt lgkmcnt(5)
	v_mov_b32_e32 v20, v6
	v_mov_b32_e32 v21, v7
	s_waitcnt lgkmcnt(0)
	v_mfma_scale_f32_32x32x64_f8f6f4 v[32:47], v[0:5], v[120:125], 0, v162, v162 op_sel_hi:[0,0,0] cbsz:2 blgp:2
	s_mov_b32 s12, s13
	s_mov_b32 s14, s13
	s_mov_b32 s15, s13
	s_mov_b32 s16, s13
	s_mov_b32 s17, s13
	s_mov_b32 s18, s13
	s_mov_b32 s19, s13
	v_mfma_scale_f32_32x32x64_f8f6f4 v[16:31], v[16:21], v[120:125], 0, v162, v162 op_sel_hi:[0,0,0] cbsz:2 blgp:2
	s_mov_b32 s20, s13
	s_mov_b32 s21, s13
	s_mov_b32 s22, s13
	s_mov_b32 s23, s13
	s_mov_b32 s24, s13
	s_mov_b32 s25, s13
	s_mov_b32 s26, s13
	s_mov_b32 s27, s13
	v_mov_b64_e32 v[0:1], s[12:13]
	v_and_b32_e32 v169, 63, v166
	v_lshlrev_b32_e32 v174, 10, v48
	s_mov_b32 s53, 4
	v_mov_b64_e32 v[2:3], s[14:15]
	v_mov_b64_e32 v[4:5], s[16:17]
	v_mov_b64_e32 v[6:7], s[18:19]
	v_mov_b64_e32 v[8:9], s[20:21]
	v_mov_b64_e32 v[10:11], s[22:23]
	v_mov_b64_e32 v[12:13], s[24:25]
	v_mov_b64_e32 v[14:15], s[26:27]
	v_mov_b32_e32 v54, v60
	v_mov_b32_e32 v55, v61
	v_mov_b32_e32 v60, v62
	v_mov_b32_e32 v61, v63
	v_add_u32_e32 v49, 0x2000, v49
	v_mfma_scale_f32_32x32x64_f8f6f4 v[32:47], v[50:55], v[126:131], v[32:47], v162, v162 op_sel_hi:[0,0,0] cbsz:2 blgp:2
	ds_read_b128 v[50:53], v173 offset:6144
	ds_read_b128 v[62:65], v173 offset:6656
	ds_read2_b64 v[66:69], v49 offset1:32
	v_mfma_scale_f32_32x32x64_f8f6f4 v[16:31], v[56:61], v[126:131], v[16:31], v162, v162 op_sel_hi:[0,0,0] cbsz:2 blgp:2
	s_waitcnt lgkmcnt(0)
	v_mov_b32_e32 v54, v66
	v_mov_b32_e32 v55, v67
	v_mov_b32_e32 v66, v68
	v_mov_b32_e32 v67, v69
	v_mfma_scale_f32_32x32x64_f8f6f4 v[32:47], v[50:55], v[132:137], v[32:47], v162, v162 op_sel_hi:[0,0,0] cbsz:2 blgp:2
	s_nop 0
	v_mfma_scale_f32_32x32x64_f8f6f4 v[16:31], v[62:67], v[132:137], v[16:31], v162, v162 op_sel_hi:[0,0,0] cbsz:2 blgp:2
	s_nop 9
	v_max_f32_e32 v49, v33, v33
	v_max_f32_e32 v50, v32, v32
	v_max_f32_e32 v49, v50, v49
	v_max3_f32 v49, v49, v34, v35
	v_max3_f32 v49, v49, v36, v37
	v_max3_f32 v49, v49, v38, v39
	v_max3_f32 v49, v49, v40, v41
	v_max3_f32 v49, v49, v42, v43
	v_max3_f32 v49, v49, v44, v45
	v_max3_f32 v49, v49, v46, v47
	v_max3_f32 v49, v49, v16, v17
	v_max3_f32 v49, v49, v18, v19
	v_max3_f32 v49, v49, v20, v21
	v_max3_f32 v49, v49, v22, v23
	v_max3_f32 v49, v49, v24, v25
	v_max3_f32 v49, v49, v26, v27
	v_max3_f32 v49, v49, v28, v29
	v_max3_f32 v49, v49, v30, v31
	v_mov_b32_e32 v50, v49
	s_nop 1
	v_permlane32_swap_b32_e32 v49, v50
	v_max_f32_e32 v50, v50, v50
	v_max_f32_e32 v49, v49, v49
	v_max_f32_e32 v49, v49, v50
	v_add_f32_e32 v50, 0x7149f2ca, v49
	v_max_f32_e32 v49, 0xf149f2ca, v49
	v_sub_f32_e32 v51, 0xf149f2ca, v49
	v_mul_f32_e32 v51, 0x3dd53b94, v51
	v_cmp_ge_f32_e32 vcc, s69, v50
	v_exp_f32_e32 v51, v51
	s_cmp_eq_u64 vcc, exec
	s_cselect_b64 vcc, -1, 0
	v_cndmask_b32_e32 v181, v49, v163, vcc
	v_fmamk_f32 v50, v181, 0xbdd53b94, v164
	v_pk_fma_f32 v[32:33], v[32:33], s[50:51], v[50:51] op_sel_hi:[1,0,0]
	v_pk_fma_f32 v[34:35], v[34:35], s[50:51], v[50:51] op_sel_hi:[1,0,0]
	v_pk_fma_f32 v[36:37], v[36:37], s[50:51], v[50:51] op_sel_hi:[1,0,0]
	v_pk_fma_f32 v[38:39], v[38:39], s[50:51], v[50:51] op_sel_hi:[1,0,0]
	v_pk_fma_f32 v[40:41], v[40:41], s[50:51], v[50:51] op_sel_hi:[1,0,0]
	v_pk_fma_f32 v[42:43], v[42:43], s[50:51], v[50:51] op_sel_hi:[1,0,0]
	v_pk_fma_f32 v[44:45], v[44:45], s[50:51], v[50:51] op_sel_hi:[1,0,0]
	v_pk_fma_f32 v[46:47], v[46:47], s[50:51], v[50:51] op_sel_hi:[1,0,0]
	v_exp_f32_e32 v65, v32
	v_exp_f32_e32 v197, v33
	v_exp_f32_e32 v187, v34
	v_exp_f32_e32 v189, v35
	v_exp_f32_e32 v195, v36
	v_exp_f32_e32 v196, v37
	v_exp_f32_e32 v191, v38
	v_exp_f32_e32 v192, v39
	v_exp_f32_e32 v193, v40
	v_exp_f32_e32 v194, v41
	v_exp_f32_e32 v183, v42
	v_exp_f32_e32 v184, v43
	v_exp_f32_e32 v188, v44
	v_exp_f32_e32 v190, v45
	v_exp_f32_e32 v185, v46
	v_exp_f32_e32 v186, v47
	s_add_u32 s8, s30, s8
	v_cndmask_b32_e64 v179, v51, 1.0, vcc
	v_pk_fma_f32 v[148:149], v[30:31], s[50:51], v[50:51] op_sel_hi:[1,0,0]
	v_pk_fma_f32 v[150:151], v[28:29], s[50:51], v[50:51] op_sel_hi:[1,0,0]
	v_pk_fma_f32 v[152:153], v[26:27], s[50:51], v[50:51] op_sel_hi:[1,0,0]
	v_pk_fma_f32 v[154:155], v[24:25], s[50:51], v[50:51] op_sel_hi:[1,0,0]
	v_pk_fma_f32 v[156:157], v[22:23], s[50:51], v[50:51] op_sel_hi:[1,0,0]
	v_pk_fma_f32 v[82:83], v[20:21], s[50:51], v[50:51] op_sel_hi:[1,0,0]
	v_pk_fma_f32 v[158:159], v[18:19], s[50:51], v[50:51] op_sel_hi:[1,0,0]
	v_pk_fma_f32 v[160:161], v[16:17], s[50:51], v[50:51] op_sel_hi:[1,0,0]
	v_lshlrev_b32_e32 v177, 4, v48
	s_addc_u32 s9, s31, 0
	v_mov_b64_e32 v[62:63], v[14:15]
	v_mov_b64_e32 v[30:31], v[14:15]
	v_mov_b64_e32 v[46:47], v[14:15]
	v_lshl_add_u64 v[142:143], s[6:7], 0, v[138:139]
	v_lshl_add_u64 v[144:145], s[34:35], 0, v[138:139]
	v_cmp_gt_u32_e64 s[6:7], 32, v169
	v_lshl_add_u32 v178, v167, 2, v171
	v_lshl_add_u64 v[146:147], s[8:9], 0, v[138:139]
	v_mov_b32_e32 v180, 0
	s_mov_b64 s[14:15], 0x89dc400
	v_mov_b64_e32 v[60:61], v[12:13]
	v_mov_b64_e32 v[58:59], v[10:11]
	v_mov_b64_e32 v[56:57], v[8:9]
	v_mov_b64_e32 v[54:55], v[6:7]
	v_mov_b64_e32 v[52:53], v[4:5]
	v_mov_b64_e32 v[50:51], v[2:3]
	v_mov_b64_e32 v[48:49], v[0:1]
	v_mov_b64_e32 v[28:29], v[12:13]
	v_mov_b64_e32 v[26:27], v[10:11]
	v_mov_b64_e32 v[24:25], v[8:9]
	v_mov_b64_e32 v[22:23], v[6:7]
	v_mov_b64_e32 v[20:21], v[4:5]
	v_mov_b64_e32 v[18:19], v[2:3]
	v_mov_b64_e32 v[16:17], v[0:1]
	v_mov_b64_e32 v[44:45], v[12:13]
	v_mov_b64_e32 v[42:43], v[10:11]
	v_mov_b64_e32 v[40:41], v[8:9]
	v_mov_b64_e32 v[38:39], v[6:7]
	v_mov_b64_e32 v[36:37], v[4:5]
	v_mov_b64_e32 v[34:35], v[2:3]
	v_mov_b64_e32 v[32:33], v[0:1]
	v_mov_b32_e32 v232, v112
	v_mov_b32_e32 v233, v112
	v_mov_b32_e32 v234, v112
	v_mov_b32_e32 v235, v112
	v_mov_b32_e32 v236, v112
	v_mov_b32_e32 v237, v112
	v_mov_b32_e32 v238, v112
	v_mov_b32_e32 v239, v112

; template <bool FUSE>
; DEVINL void qkt(f32x16& p0, f32x16& p1, const char* Ks, const i32x8* q8, int r32, int hi, f32x16& e1) {
;   p0 = f32x16{}; p1 = f32x16{};
;   const char* ka = Ks + hi * 1024 + r32 * 16; const char* kb = Ks + 4096 + hi * 512 + r32 * 8;
;   const char* ra = Ks + 6144 + hi * 1024 + r32 * 16; const char* rb = Ks + 6144 + 2048 + hi * 512 + r32 * 8;
;   u32x4 fa[3][2]; u32x2 fb[3][2];
;     ...
;   QK_LD(0, 0);
; #pragma unroll
;   for (int t = 0; t < 3; ++t) {
;     if (t + 1 < 3) QK_LD(t + 1, (t + 1) % 3);
;     const i32x8 a0 = mk6((int)fa[t][0][0], (int)fa[t][0][1], (int)fa[t][0][2], (int)fa[t][0][3], (int)fb[t][0][0], (int)fb[t][0][1]);
; DEVINL void pv_psm(f32x16* o, const VFrag& f, const i32x8& pa, f32x16& lsum, const i32x8& ones8,
;                    f32x16& p0, f32x16& p1, float& m_reg, float& mn, float& alpha, int kvalid, int hi) {
;   constexpr float C = MLA_SCALE * 1.4426950408889634f;
;     ...
;   if (kvalid < 64) {
; #pragma unroll
;     for (int r = 0; r < 16; ++r) { if (crow(r, hi) >= kvalid) p0[r] = -1e30f; if (32 + crow(r, hi) >= kvalid) p1[r] = -1e30f; }
;   }
;   PVM(0);
;   float pmax = p0[0];
; #pragma unroll
;   for (int r = 1; r < 16; ++r) pmax = fmaxf(pmax, p0[r]);
;   SBAR();
;   PVM(1);
; #pragma unroll
;   for (int r = 0; r < 16; ++r) pmax = fmaxf(pmax, p1[r]);
;   { auto rr = __builtin_amdgcn_permlane32_swap(__float_as_uint(pmax), __float_as_uint(pmax), false, false);
;     pmax = fmaxf(__uint_as_float(rr[0]), __uint_as_float(rr[1])); }
;   SBAR();
;   PVM(2);
;   if (__builtin_expect(__all(pmax - m_reg <= THR / MLA_SCALE), 1)) { mn = m_reg; alpha = 1.f; }
;   else { mn = fmaxf(m_reg, pmax); alpha = __builtin_amdgcn_exp2f((m_reg - mn) * C); m_reg = mn; }
;   const float mnC = PSHIFT - mn * C;
;   const f32x2 C2 = {C, C}, M2 = {mnC, mnC};
; #pragma unroll
;   for (int r = 0; r < 16; r += 2) { f32x2 v = {p0[r], p0[r + 1]}; v = __builtin_elementwise_fma(v, C2, M2); p0[r] = v[0]; p0[r + 1] = v[1]; }
;   SBAR();
;   PVM(3);
; #pragma unroll
;   for (int r = 0; r < 16; r += 2) { f32x2 v = {p1[r], p1[r + 1]}; v = __builtin_elementwise_fma(v, C2, M2); p1[r] = v[0]; p1[r + 1] = v[1]; }
; #pragma unroll
;   for (int r = 0; r < 8; ++r) p0[r] = __builtin_amdgcn_exp2f(p0[r]);
;   SBAR();
;   lsum = MFMA8(ones8, pa, (f32x16{}));
; #pragma unroll
;   for (int r = 8; r < 16; ++r) p0[r] = __builtin_amdgcn_exp2f(p0[r]);
;   SBAR();
;     ...
; }
.LBB0_568:
	s_or_b64 exec, exec, s[8:9]
	s_add_i32 s19, s53, -2
	s_and_b32 s20, s19, 3
	v_lshl_add_u32 v64, s20, 13, v172
	v_add_u32_e32 v64, 0x9000, v64
	v_lshl_add_u64 v[66:67], v[146:147], 0, s[14:15]
	v_readfirstlane_b32 s8, v64
	v_lshl_add_u32 v64, s16, 13, v172
	v_add_u32_e32 v64, 0x9000, v64
	s_mov_b32 m0, s8
	s_lshl_b32 s12, s17, 13
	v_readfirstlane_b32 s8, v64
	global_load_lds_dwordx4 v[66:67], off
	v_lshl_add_u64 v[66:67], v[140:141], 0, s[12:13]
	s_mov_b32 m0, s8
	s_nop 0
	global_load_lds_dwordx4 v[66:67], off
	s_and_b32 s12, s18, 3
	s_mul_i32 s8, s12, 0x2400
	s_add_i32 s8, s8, 0
	v_add3_u32 v64, s8, v170, v176
	v_add_u32_e32 v80, 0x1000, v64
	ds_read_b64 v[70:71], v80
	ds_read_b64 v[76:77], v80 offset:256
	v_add3_u32 v113, s8, v174, v175
	ds_read_b128 v[66:69], v113
	ds_read_b128 v[72:75], v113 offset:512
	ds_read_b128 v[114:117], v113 offset:2048
	ds_read_b128 v[198:201], v113 offset:2560
	ds_read_b64 v[118:119], v80 offset:1024
	ds_read_b64 v[202:203], v80 offset:1280
	v_exp_f32_e32 v182, v82
	s_waitcnt lgkmcnt(0)
	v_exp_f32_e32 v214, v83
	v_mfma_scale_f32_32x32x64_f8f6f4 v[96:111], v[66:71], v[120:125], 0, v162, v162 op_sel_hi:[0,0,0] cbsz:2 blgp:2
	v_exp_f32_e32 v160, v160
	v_exp_f32_e32 v161, v161
	v_exp_f32_e32 v158, v158
	v_exp_f32_e32 v159, v159
	v_mfma_scale_f32_32x32x64_f8f6f4 v[80:95], v[72:77], v[120:125], 0, v162, v162 op_sel_hi:[0,0,0] cbsz:2 blgp:2
	ds_read_b128 v[66:69], v113 offset:6144
	ds_read_b128 v[72:75], v113 offset:6656
	v_mfma_scale_f32_32x32x64_f8f6f4 v[96:111], v[114:119], v[126:131], v[96:111], v162, v162 op_sel_hi:[0,0,0] cbsz:2 blgp:2
	v_add_u32_e32 v64, 0x2000, v64
	ds_read_b64 v[70:71], v64
	ds_read_b64 v[76:77], v64 offset:256
	v_exp_f32_e32 v113, v156
	v_exp_f32_e32 v114, v157
	v_exp_f32_e32 v115, v154
	v_exp_f32_e32 v116, v155
	v_exp_f32_e32 v117, v152
	v_mfma_scale_f32_32x32x64_f8f6f4 v[80:95], v[198:203], v[126:131], v[80:95], v162, v162 op_sel_hi:[0,0,0] cbsz:2 blgp:2
	v_exp_f32_e32 v118, v153
	s_waitcnt lgkmcnt(0)
	v_exp_f32_e32 v119, v150
	v_mfma_scale_f32_32x32x64_f8f6f4 v[96:111], v[66:71], v[132:137], v[96:111], v162, v162 op_sel_hi:[0,0,0] cbsz:2 blgp:2
	v_exp_f32_e32 v156, v151
	v_exp_f32_e32 v157, v148
	v_exp_f32_e32 v215, v149
	v_mfma_scale_f32_32x32x64_f8f6f4 v[80:95], v[72:77], v[132:137], v[80:95], v162, v162 op_sel_hi:[0,0,0] cbsz:2 blgp:2
	s_add_i32 s8, s14, 0xf762bc00
	s_and_b32 s8, s8, 0x6000
	v_add_u32_e32 v64, s8, v173
	ds_read_b128 v[72:75], v64 offset:36864
	ds_read_b128 v[76:79], v64 offset:37376
	ds_read_b128 v[148:151], v64 offset:38912
	ds_read_b128 v[152:155], v64 offset:39424
	ds_read_b128 v[198:201], v64 offset:40960
	ds_read_b128 v[202:205], v64 offset:41472
	ds_read_b128 v[206:209], v64 offset:43008
	ds_read_b128 v[210:213], v64 offset:43520
	v_cvt_pk_fp8_f32 v64, v65, v197
	v_cvt_pk_fp8_f32 v68, v160, v161
	v_cvt_pk_fp8_f32 v65, v195, v196
	v_cvt_pk_fp8_f32 v69, v182, v214
	v_cvt_pk_fp8_f32 v66, v193, v194
	v_cvt_pk_fp8_f32 v70, v115, v116
	v_cvt_pk_fp8_f32 v67, v188, v190
	v_cvt_pk_fp8_f32 v71, v119, v156
	v_cvt_pk_fp8_f32 v64, v187, v189 op_sel:[0,0,1]
	v_cvt_pk_fp8_f32 v68, v158, v159 op_sel:[0,0,1]
	v_cvt_pk_fp8_f32 v65, v191, v192 op_sel:[0,0,1]
	v_cvt_pk_fp8_f32 v69, v113, v114 op_sel:[0,0,1]
	v_cvt_pk_fp8_f32 v66, v183, v184 op_sel:[0,0,1]
	v_cvt_pk_fp8_f32 v70, v117, v118 op_sel:[0,0,1]
	v_cvt_pk_fp8_f32 v67, v185, v186 op_sel:[0,0,1]
	v_cvt_pk_fp8_f32 v71, v157, v215 op_sel:[0,0,1]
	s_waitcnt lgkmcnt(0)
	s_nop 0
	v_mfma_scale_f32_32x32x64_f8f6f4 v[0:15], v[64:71], v[72:79], v[0:15], v162, v162 op_sel_hi:[0,0,0]
	v_max_f32_e32 v113, v96, v97
	v_max3_f32 v113, v113, v98, v99
	v_max3_f32 v113, v113, v100, v101
	v_max3_f32 v113, v113, v102, v103
	v_max3_f32 v113, v113, v104, v105
	v_max3_f32 v113, v113, v106, v107
	v_max3_f32 v113, v113, v108, v109
	v_max3_f32 v113, v113, v110, v111
	v_mfma_scale_f32_32x32x64_f8f6f4 v[48:63], v[64:71], v[148:155], v[48:63], v162, v162 op_sel_hi:[0,0,0]
	v_max3_f32 v72, v113, v80, v81
	v_max3_f32 v72, v72, v82, v83
	v_max3_f32 v72, v72, v84, v85
	v_max3_f32 v72, v72, v86, v87
	v_max3_f32 v72, v72, v88, v89
	v_max3_f32 v72, v72, v90, v91
	v_max3_f32 v72, v72, v92, v93
	v_max3_f32 v72, v72, v94, v95
	v_mov_b32_e32 v73, v72
	s_nop 1
	v_permlane32_swap_b32_e32 v72, v73
	v_max_f32_e32 v72, v72, v73
	v_mfma_scale_f32_32x32x64_f8f6f4 v[16:31], v[64:71], v[198:205], v[16:31], v162, v162 op_sel_hi:[0,0,0]
	v_max_f32_e32 v148, v181, v72
	v_sub_f32_e32 v73, v72, v181
	v_sub_f32_e32 v72, v181, v148
	v_mul_f32_e32 v72, 0x3dd53b94, v72
	v_exp_f32_e32 v72, v72
	v_cmp_ge_f32_e32 vcc, s69, v73
	s_cmp_eq_u64 vcc, exec
	s_cselect_b64 s[8:9], -1, 0
	v_cndmask_b32_e64 v182, v72, 1.0, s[8:9]
	v_mfma_scale_f32_32x32x64_f8f6f4 v[32:47], v[64:71], v[206:213], v[32:47], v162, v162 op_sel_hi:[0,0,0]
	v_mfma_scale_f32_32x32x64_f8f6f4 v[240:255], v[232:239], v[64:71], 0, v162, v162 op_sel_hi:[0,0,0]
	v_cmp_gt_f32_e32 vcc, 1.0, v182
	s_cbranch_vccz .LBB0_572
	s_and_saveexec_b64 s[16:17], s[6:7]
	ds_write_b32 v178, v182 offset:128
	s_or_b64 exec, exec, s[16:17]
	s_waitcnt lgkmcnt(0)
	v_add_u32_e32 v113, v171, v177
	ds_read_b128 v[72:75], v113 offset:224
	ds_read_b128 v[76:79], v113 offset:192
	ds_read_b128 v[114:117], v113 offset:160
	ds_read_b128 v[150:153], v113 offset:128
	s_waitcnt lgkmcnt(0)
	v_pk_mul_f32 v[12:13], v[12:13], v[72:73]
	v_pk_mul_f32 v[8:9], v[8:9], v[76:77]
	v_pk_mul_f32 v[4:5], v[4:5], v[114:115]
	v_pk_mul_f32 v[14:15], v[14:15], v[74:75]
	v_pk_mul_f32 v[10:11], v[10:11], v[78:79]
	v_pk_mul_f32 v[6:7], v[6:7], v[116:117]
	v_pk_mul_f32 v[2:3], v[2:3], v[152:153]
	v_pk_mul_f32 v[0:1], v[0:1], v[150:151]
	v_pk_mul_f32 v[60:61], v[60:61], v[72:73]
	v_pk_mul_f32 v[56:57], v[56:57], v[76:77]
	v_pk_mul_f32 v[52:53], v[52:53], v[114:115]
	v_pk_mul_f32 v[62:63], v[62:63], v[74:75]
	v_pk_mul_f32 v[58:59], v[58:59], v[78:79]
	v_pk_mul_f32 v[54:55], v[54:55], v[116:117]
	v_pk_mul_f32 v[50:51], v[50:51], v[152:153]
	v_pk_mul_f32 v[48:49], v[48:49], v[150:151]
	v_pk_mul_f32 v[28:29], v[28:29], v[72:73]
	v_pk_mul_f32 v[24:25], v[24:25], v[76:77]
	v_pk_mul_f32 v[20:21], v[20:21], v[114:115]
	v_pk_mul_f32 v[30:31], v[30:31], v[74:75]
	v_pk_mul_f32 v[26:27], v[26:27], v[78:79]
	v_pk_mul_f32 v[22:23], v[22:23], v[116:117]
	v_pk_mul_f32 v[18:19], v[18:19], v[152:153]
	v_pk_mul_f32 v[16:17], v[16:17], v[150:151]
	v_pk_mul_f32 v[44:45], v[44:45], v[72:73]
	v_pk_mul_f32 v[40:41], v[40:41], v[76:77]
	v_pk_mul_f32 v[36:37], v[36:37], v[114:115]
	v_pk_mul_f32 v[46:47], v[46:47], v[74:75]
	v_pk_mul_f32 v[42:43], v[42:43], v[78:79]
	v_pk_mul_f32 v[38:39], v[38:39], v[116:117]
	v_pk_mul_f32 v[34:35], v[34:35], v[152:153]
	v_pk_mul_f32 v[32:33], v[32:33], v[150:151]
; #define SBAR() __builtin_amdgcn_sched_barrier(0)
; #define MFMA8(A, B, C) __builtin_amdgcn_mfma_scale_f32_32x32x64_f8f6f4(A, B, C, 0, 0, 0, 0x7f7f7f7f, 0, 0x7f7f7f7f)
; template <bool FUSE>
; DEVINL void qkt(f32x16& p0, f32x16& p1, const char* Ks, const i32x8* q8, int r32, int hi, f32x16& e1) {
;   p0 = f32x16{}; p1 = f32x16{};
;   const char* ka = Ks + hi * 1024 + r32 * 16; const char* kb = Ks + 4096 + hi * 512 + r32 * 8;
;   const char* ra = Ks + 6144 + hi * 1024 + r32 * 16; const char* rb = Ks + 6144 + 2048 + hi * 512 + r32 * 8;
;   u32x4 fa[3][2]; u32x2 fb[3][2];
;     ...
;   QK_LD(0, 0);
; #pragma unroll
;   for (int t = 0; t < 3; ++t) {
;     if (t + 1 < 3) QK_LD(t + 1, (t + 1) % 3);
;     const i32x8 a0 = mk6((int)fa[t][0][0], (int)fa[t][0][1], (int)fa[t][0][2], (int)fa[t][0][3], (int)fb[t][0][0], (int)fb[t][0][1]);
;     const i32x8 a1 = mk6((int)fa[t][1][0], (int)fa[t][1][1], (int)fa[t][1][2], (int)fa[t][1][3], (int)fb[t][1][0], (int)fb[t][1][1]);
;     p0 = MFMA6(a0, q8[t], p0);
;     if (FUSE) {
; #pragma unroll
;       for (int r = 0; r < 3; ++r) { const int rr = t * 6 + r; if (rr < 16) e1[rr] = __builtin_amdgcn_exp2f(e1[rr]); }
;     }
;     p1 = MFMA6(a1, q8[t], p1);
;     if (FUSE) {
; #pragma unroll
;       for (int r = 3; r < 6; ++r) { const int rr = t * 6 + r; if (rr < 16) e1[rr] = __builtin_amdgcn_exp2f(e1[rr]); }
;     }
;     SBAR();
;   }
;     ...
; }
; DEVINL void pv_psm(f32x16* o, const VFrag& f, const i32x8& pa, f32x16& lsum, const i32x8& ones8,
;                    f32x16& p0, f32x16& p1, float& m_reg, float& mn, float& alpha, int kvalid, int hi) {
;     ...
;   else { mn = fmaxf(m_reg, pmax); alpha = __builtin_amdgcn_exp2f((m_reg - mn) * C); m_reg = mn; }
;   const float mnC = PSHIFT - mn * C;
;   const f32x2 C2 = {C, C}, M2 = {mnC, mnC};
; #pragma unroll
;   for (int r = 0; r < 16; r += 2) { f32x2 v = {p0[r], p0[r + 1]}; v = __builtin_elementwise_fma(v, C2, M2); p0[r] = v[0]; p0[r + 1] = v[1]; }
;   SBAR();
;   PVM(3);
; #pragma unroll
;   for (int r = 0; r < 16; r += 2) { f32x2 v = {p1[r], p1[r + 1]}; v = __builtin_elementwise_fma(v, C2, M2); p1[r] = v[0]; p1[r + 1] = v[1]; }
; #pragma unroll
;   for (int r = 0; r < 8; ++r) p0[r] = __builtin_amdgcn_exp2f(p0[r]);
;   SBAR();
;   lsum = MFMA8(ones8, pa, (f32x16{}));
; #pragma unroll
;   for (int r = 8; r < 16; ++r) p0[r] = __builtin_amdgcn_exp2f(p0[r]);
.LBB0_572:
	v_cndmask_b32_e64 v227, v148, v181, s[8:9]
	v_fmamk_f32 v230, v227, 0xbdd53b94, v164
	v_pk_fma_f32 v[76:77], v[104:105], s[50:51], v[230:231] op_sel_hi:[1,0,0]
	v_pk_fma_f32 v[68:69], v[96:97], s[50:51], v[230:231] op_sel_hi:[1,0,0]
	v_exp_f32_e32 v198, v77
	v_pk_fma_f32 v[70:71], v[98:99], s[50:51], v[230:231] op_sel_hi:[1,0,0]
	v_pk_fma_f32 v[72:73], v[100:101], s[50:51], v[230:231] op_sel_hi:[1,0,0]
	v_pk_fma_f32 v[74:75], v[102:103], s[50:51], v[230:231] op_sel_hi:[1,0,0]
	v_pk_fma_f32 v[78:79], v[106:107], s[50:51], v[230:231] op_sel_hi:[1,0,0]
	v_pk_fma_f32 v[96:97], v[108:109], s[50:51], v[230:231] op_sel_hi:[1,0,0]
	v_pk_fma_f32 v[98:99], v[110:111], s[50:51], v[230:231] op_sel_hi:[1,0,0]
	v_pk_fma_f32 v[102:103], v[80:81], s[50:51], v[230:231] op_sel_hi:[1,0,0]
	v_pk_fma_f32 v[114:115], v[82:83], s[50:51], v[230:231] op_sel_hi:[1,0,0]
	v_pk_fma_f32 v[116:117], v[84:85], s[50:51], v[230:231] op_sel_hi:[1,0,0]
	v_pk_fma_f32 v[228:229], v[86:87], s[50:51], v[230:231] op_sel_hi:[1,0,0]
	v_pk_fma_f32 v[156:157], v[88:89], s[50:51], v[230:231] op_sel_hi:[1,0,0]
	v_exp_f32_e32 v113, v68
	v_exp_f32_e32 v181, v69
	v_exp_f32_e32 v183, v70
	v_exp_f32_e32 v192, v71
	v_exp_f32_e32 v193, v72
	v_exp_f32_e32 v194, v73
	v_exp_f32_e32 v195, v74
	v_exp_f32_e32 v196, v75
	v_exp_f32_e32 v197, v76
	v_exp_f32_e32 v199, v78
	v_exp_f32_e32 v216, v79
	v_exp_f32_e32 v217, v96
	v_exp_f32_e32 v218, v97
	v_exp_f32_e32 v219, v98
	v_exp_f32_e32 v220, v99
	v_pk_fma_f32 v[158:159], v[90:91], s[50:51], v[230:231] op_sel_hi:[1,0,0]
	v_pk_fma_f32 v[160:161], v[92:93], s[50:51], v[230:231] op_sel_hi:[1,0,0]
	v_pk_fma_f32 v[184:185], v[94:95], s[50:51], v[230:231] op_sel_hi:[1,0,0]
	s_mulk_i32 s20, 0x2400
	s_add_i32 s8, s20, 0
	v_add3_u32 v152, s8, v170, v176
	v_add_u32_e32 v72, 0x1000, v152
	ds_read_b64 v[70:71], v72
	ds_read_b64 v[86:87], v72 offset:256
	v_add3_u32 v148, s8, v174, v175
	ds_read_b128 v[66:69], v148
	ds_read_b128 v[82:85], v148 offset:512
	ds_read_b128 v[98:101], v148 offset:2048
	ds_read_b128 v[104:107], v148 offset:2560
	v_exp_f32_e32 v221, v102
	v_exp_f32_e32 v222, v103
	ds_read_b64 v[102:103], v72 offset:1024
	ds_read_b64 v[108:109], v72 offset:1280
	s_waitcnt lgkmcnt(0)
	v_mfma_scale_f32_32x32x64_f8f6f4 v[66:81], v[66:71], v[120:125], 0, v162, v162 op_sel_hi:[0,0,0] cbsz:2 blgp:2
	v_exp_f32_e32 v223, v114
	v_exp_f32_e32 v224, v115
	v_exp_f32_e32 v225, v116
	v_exp_f32_e32 v226, v117
	v_mfma_scale_f32_32x32x64_f8f6f4 v[82:97], v[82:87], v[120:125], 0, v162, v162 op_sel_hi:[0,0,0] cbsz:2 blgp:2
	v_add_u32_e32 v110, 0x2000, v152
	ds_read_b128 v[114:117], v148 offset:6144
	ds_read_b128 v[148:151], v148 offset:6656
	ds_read_b64 v[118:119], v110
	ds_read_b64 v[152:153], v110 offset:256
	v_mfma_scale_f32_32x32x64_f8f6f4 v[66:81], v[98:103], v[126:131], v[66:81], v162, v162 op_sel_hi:[0,0,0] cbsz:2 blgp:2
	v_exp_f32_e32 v100, v228
	v_exp_f32_e32 v101, v229
	v_exp_f32_e32 v110, v156
	v_exp_f32_e32 v111, v157
	v_exp_f32_e32 v156, v158
	v_exp_f32_e32 v157, v159
	v_mfma_scale_f32_32x32x64_f8f6f4 v[82:97], v[104:109], v[126:131], v[82:97], v162, v162 op_sel_hi:[0,0,0] cbsz:2 blgp:2
	s_waitcnt lgkmcnt(0)
	v_exp_f32_e32 v106, v160
	v_mfma_scale_f32_32x32x64_f8f6f4 v[66:81], v[114:119], v[132:137], v[66:81], v162, v162 op_sel_hi:[0,0,0] cbsz:2 blgp:2
	v_exp_f32_e32 v107, v161
	v_exp_f32_e32 v108, v184
	v_exp_f32_e32 v109, v185
	v_mfma_scale_f32_32x32x64_f8f6f4 v[82:97], v[148:153], v[132:137], v[82:97], v162, v162 op_sel_hi:[0,0,0] cbsz:2 blgp:2
	v_lshl_add_u32 v98, s12, 13, v173
	ds_read_b128 v[148:151], v98 offset:36864
	ds_read_b128 v[152:155], v98 offset:37376
	ds_read_b128 v[184:187], v98 offset:38912
	ds_read_b128 v[188:191], v98 offset:39424
	ds_read_b128 v[200:203], v98 offset:40960
	ds_read_b128 v[204:207], v98 offset:41472
	ds_read_b128 v[208:211], v98 offset:43008
	ds_read_b128 v[212:215], v98 offset:43520
	v_cvt_pk_fp8_f32 v103, v225, v226
	v_cvt_pk_fp8_f32 v98, v113, v181
	v_cvt_pk_fp8_f32 v102, v221, v222
	v_cvt_pk_fp8_f32 v99, v193, v194
	v_cvt_pk_fp8_f32 v103, v100, v101 op_sel:[0,0,1]
	v_cvt_pk_fp8_f32 v100, v197, v198
	v_cvt_pk_fp8_f32 v104, v110, v111
	v_cvt_pk_fp8_f32 v101, v217, v218
	v_cvt_pk_fp8_f32 v105, v106, v107
	v_cvt_pk_fp8_f32 v98, v183, v192 op_sel:[0,0,1]
	v_cvt_pk_fp8_f32 v102, v223, v224 op_sel:[0,0,1]
	v_cvt_pk_fp8_f32 v99, v195, v196 op_sel:[0,0,1]
	v_cvt_pk_fp8_f32 v100, v199, v216 op_sel:[0,0,1]
	v_cvt_pk_fp8_f32 v104, v156, v157 op_sel:[0,0,1]
	v_cvt_pk_fp8_f32 v101, v219, v220 op_sel:[0,0,1]
	v_cvt_pk_fp8_f32 v105, v108, v109 op_sel:[0,0,1]
	s_waitcnt lgkmcnt(0)
	s_nop 0
	v_mfma_scale_f32_32x32x64_f8f6f4 v[0:15], v[98:105], v[148:155], v[0:15], v162, v162 op_sel_hi:[0,0,0]
	s_cmpk_gt_u32 s19, 0xff
	s_cbranch_scc1 .Lmask_last
; DEVINL int crow(int r, int hi) { return (r & 3) + 8 * (r >> 2) + 4 * hi; }
; #define SBAR() __builtin_amdgcn_sched_barrier(0)
; #define PVM(db) do { const i32x8 b = {(int)f.v[db][0][0], (int)f.v[db][0][1], (int)f.v[db][0][2], (int)f.v[db][0][3], (int)f.v[db][1][0], (int)f.v[db][1][1], (int)f.v[db][1][2], (int)f.v[db][1][3]}; \
;     o[db] = MFMA8(pa, b, o[db]); } while (0)
; DEVINL void pv_psm(f32x16* o, const VFrag& f, const i32x8& pa, f32x16& lsum, const i32x8& ones8,
;                    f32x16& p0, f32x16& p1, float& m_reg, float& mn, float& alpha, int kvalid, int hi) {
;     ...
;   if (kvalid < 64) {
; #pragma unroll
;     for (int r = 0; r < 16; ++r) { if (crow(r, hi) >= kvalid) p0[r] = -1e30f; if (32 + crow(r, hi) >= kvalid) p1[r] = -1e30f; }
;   }
;   PVM(0);
;   float pmax = p0[0];
; #pragma unroll
;   for (int r = 1; r < 16; ++r) pmax = fmaxf(pmax, p0[r]);
;   SBAR();
;   PVM(1);
; #pragma unroll
;   for (int r = 0; r < 16; ++r) pmax = fmaxf(pmax, p1[r]);
;   { auto rr = __builtin_amdgcn_permlane32_swap(__float_as_uint(pmax), __float_as_uint(pmax), false, false);
;     pmax = fmaxf(__uint_as_float(rr[0]), __uint_as_float(rr[1])); }
;   SBAR();
;   PVM(2);
;   if (__builtin_expect(__all(pmax - m_reg <= THR / MLA_SCALE), 1)) { mn = m_reg; alpha = 1.f; }
;   else { mn = fmaxf(m_reg, pmax); alpha = __builtin_amdgcn_exp2f((m_reg - mn) * C); m_reg = mn; }
.Lmask_ret:
	v_max_f32_e32 v241, v66, v67
	v_max3_f32 v241, v241, v68, v69
	v_max3_f32 v241, v241, v70, v71
	v_max3_f32 v241, v241, v72, v73
	v_max3_f32 v241, v241, v74, v75
	v_max3_f32 v241, v241, v76, v77
	v_max3_f32 v241, v241, v78, v79
	v_max3_f32 v241, v241, v80, v81
	v_mfma_scale_f32_32x32x64_f8f6f4 v[48:63], v[98:105], v[184:191], v[48:63], v162, v162 op_sel_hi:[0,0,0]
	v_max3_f32 v241, v241, v82, v83
	v_max3_f32 v241, v241, v84, v85
	v_max3_f32 v241, v241, v86, v87
	v_max3_f32 v241, v241, v88, v89
	v_max3_f32 v241, v241, v90, v91
	v_max3_f32 v241, v241, v92, v93
	v_max3_f32 v241, v241, v94, v95
	v_max3_f32 v241, v241, v96, v97
	v_mov_b32_e32 v242, v241
	s_nop 1
	v_permlane32_swap_b32_e32 v241, v242
	v_max_f32_e32 v241, v241, v242
	v_mfma_scale_f32_32x32x64_f8f6f4 v[16:31], v[98:105], v[200:207], v[16:31], v162, v162 op_sel_hi:[0,0,0]
	v_sub_f32_e32 v242, v241, v227
	v_max_f32_e32 v241, v227, v241
	v_sub_f32_e32 v243, v227, v241
	v_mul_f32_e32 v243, 0x3dd53b94, v243
	v_exp_f32_e32 v243, v243
	v_cmp_ge_f32_e32 vcc, s69, v242
	s_cmp_eq_u64 vcc, exec
	s_cselect_b64 s[8:9], -1, 0
	v_cndmask_b32_e64 v198, v243, 1.0, s[8:9]
	v_mfma_scale_f32_32x32x64_f8f6f4 v[32:47], v[98:105], v[208:215], v[32:47], v162, v162 op_sel_hi:[0,0,0]
	s_waitcnt vmcnt(0)
	v_cmp_gt_f32_e32 vcc, 1.0, v198
	s_waitcnt vmcnt(0)
	s_barrier
	s_cbranch_vccz .LBB0_576
	s_and_saveexec_b64 s[16:17], s[6:7]
	ds_write_b32 v178, v198 offset:128
	s_or_b64 exec, exec, s[16:17]
	s_waitcnt lgkmcnt(0)
	v_add_u32_e32 v242, v171, v177
	ds_read_b128 v[244:247], v242 offset:224
	ds_read_b128 v[116:119], v242 offset:192
	ds_read_b128 v[148:151], v242 offset:160
	ds_read_b128 v[152:155], v242 offset:128
	s_waitcnt lgkmcnt(3)
	v_pk_mul_f32 v[12:13], v[12:13], v[244:245]
	s_waitcnt lgkmcnt(2)
	v_pk_mul_f32 v[8:9], v[8:9], v[116:117]
	s_waitcnt lgkmcnt(1)
	v_pk_mul_f32 v[4:5], v[4:5], v[148:149]
	v_pk_mul_f32 v[14:15], v[14:15], v[246:247]
	v_pk_mul_f32 v[10:11], v[10:11], v[118:119]
	v_pk_mul_f32 v[6:7], v[6:7], v[150:151]
	s_waitcnt lgkmcnt(0)
	v_pk_mul_f32 v[2:3], v[2:3], v[154:155]
	v_pk_mul_f32 v[0:1], v[0:1], v[152:153]
	v_pk_mul_f32 v[60:61], v[60:61], v[244:245]
	v_pk_mul_f32 v[56:57], v[56:57], v[116:117]
	v_pk_mul_f32 v[52:53], v[52:53], v[148:149]
	v_pk_mul_f32 v[62:63], v[62:63], v[246:247]
	v_pk_mul_f32 v[58:59], v[58:59], v[118:119]
	v_pk_mul_f32 v[54:55], v[54:55], v[150:151]
	v_pk_mul_f32 v[50:51], v[50:51], v[154:155]
	v_pk_mul_f32 v[48:49], v[48:49], v[152:153]
	v_pk_mul_f32 v[28:29], v[28:29], v[244:245]
	v_pk_mul_f32 v[24:25], v[24:25], v[116:117]
	v_pk_mul_f32 v[20:21], v[20:21], v[148:149]
	v_pk_mul_f32 v[30:31], v[30:31], v[246:247]
	v_pk_mul_f32 v[26:27], v[26:27], v[118:119]
	v_pk_mul_f32 v[22:23], v[22:23], v[150:151]
	v_pk_mul_f32 v[18:19], v[18:19], v[154:155]
	v_pk_mul_f32 v[16:17], v[16:17], v[152:153]
	v_pk_mul_f32 v[44:45], v[44:45], v[244:245]
	v_pk_mul_f32 v[40:41], v[40:41], v[116:117]
	v_pk_mul_f32 v[36:37], v[36:37], v[148:149]
	v_pk_mul_f32 v[46:47], v[46:47], v[246:247]
	v_pk_mul_f32 v[42:43], v[42:43], v[118:119]
	v_pk_mul_f32 v[38:39], v[38:39], v[150:151]
	v_pk_mul_f32 v[34:35], v[34:35], v[154:155]
	v_pk_mul_f32 v[32:33], v[32:33], v[152:153]
; #define SBAR() __builtin_amdgcn_sched_barrier(0)
; #define MFMA8(A, B, C) __builtin_amdgcn_mfma_scale_f32_32x32x64_f8f6f4(A, B, C, 0, 0, 0, 0x7f7f7f7f, 0, 0x7f7f7f7f)
; #define TILE_SYNC() do { asm volatile("s_waitcnt vmcnt(0)" ::: "memory"); __syncthreads(); } while (0)
; #define RESC(a) do { if (__any((a) < 1.f)) { if (hi == 0) al_l[r32] = (a); asm volatile("s_waitcnt lgkmcnt(0)" ::: "memory"); \
;     for (int d = 0; d < 4; ++d) for (int r = 0; r < 16; ++r) o[d][r] *= al_l[crow(r, hi)]; } } while (0)
; #define LSUM() do { lsum = MFMA8(ones8, pa, (f32x16{})); } while (0)
; #define LUPD(al) do { l_reg = l_reg * (al) + lsum[0]; } while (0)
; DEVINL void pv_psm(f32x16* o, const VFrag& f, const i32x8& pa, f32x16& lsum, const i32x8& ones8,
;                    f32x16& p0, f32x16& p1, float& m_reg, float& mn, float& alpha, int kvalid, int hi) {
;     ...
;   for (int r = 0; r < 8; ++r) p0[r] = __builtin_amdgcn_exp2f(p0[r]);
;   SBAR();
;   lsum = MFMA8(ones8, pa, (f32x16{}));
; #pragma unroll
;   for (int r = 8; r < 16; ++r) p0[r] = __builtin_amdgcn_exp2f(p0[r]);
; DEVINL void mla_block(const Params& p, const bf16_t* __restrict__ Qn, const bf16_t* __restrict__ Qr, const char* __restrict__ K8, const char* __restrict__ Kp8,
;                       const char* __restrict__ V8, const bf16_t* __restrict__ Gb, bf16_t* __restrict__ Yb, char* lds, int pos0) {
;     ...
;     { const float alPrev = alB; pv_psm(o, vf, pa, lsum, ones8, pA0, pA1, m_reg, mnA, alA, L - (j + 1) * KVBLK, hi); LUPD(alPrev); }
;     TILE_SYNC(); RESC(alA);
;   }
;   pv_load(vf, VS(NT - 1), r32, hi); SBAR();
;   finishSM<false>(pA0, pA1, alA, l_reg, pa); SBAR();
;   pv_mma(o, vf, pa); LSUM(); LUPD(alA);
;   if (hi == 0) li_l[r32] = l_reg; asm volatile("s_waitcnt lgkmcnt(0)" ::: "memory");
.LBB0_576:
	v_cndmask_b32_e64 v181, v241, v227, s[8:9]
	v_fmamk_f32 v230, v181, 0xbdd53b94, v164
	v_pk_fma_f32 v[228:229], v[74:75], s[50:51], v[230:231] op_sel_hi:[1,0,0]
	v_pk_fma_f32 v[66:67], v[66:67], s[50:51], v[230:231] op_sel_hi:[1,0,0]
	v_pk_fma_f32 v[68:69], v[68:69], s[50:51], v[230:231] op_sel_hi:[1,0,0]
	v_pk_fma_f32 v[70:71], v[70:71], s[50:51], v[230:231] op_sel_hi:[1,0,0]
	v_pk_fma_f32 v[72:73], v[72:73], s[50:51], v[230:231] op_sel_hi:[1,0,0]
	v_pk_fma_f32 v[154:155], v[90:91], s[50:51], v[230:231] op_sel_hi:[1,0,0]
	v_pk_fma_f32 v[152:153], v[92:93], s[50:51], v[230:231] op_sel_hi:[1,0,0]
	v_pk_fma_f32 v[150:151], v[94:95], s[50:51], v[230:231] op_sel_hi:[1,0,0]
	v_pk_fma_f32 v[148:149], v[96:97], s[50:51], v[230:231] op_sel_hi:[1,0,0]
	v_exp_f32_e32 v65, v66
	v_exp_f32_e32 v197, v67
	v_exp_f32_e32 v187, v68
	v_exp_f32_e32 v189, v69
	v_exp_f32_e32 v195, v70
	v_exp_f32_e32 v196, v71
	v_exp_f32_e32 v191, v72
	v_exp_f32_e32 v192, v73
	v_fma_f32 v180, v179, v180, v240
	v_mfma_scale_f32_32x32x64_f8f6f4 v[240:255], v[232:239], v[98:105], 0, v162, v162 op_sel_hi:[0,0,0]
	v_fma_f32 v94, v76, s50, v230
	v_fma_f32 v95, v77, s50, v230
	v_fma_f32 v96, v78, s50, v230
	v_fma_f32 v97, v79, s50, v230
	v_fma_f32 v106, v80, s50, v230
	v_fma_f32 v107, v81, s50, v230
	v_exp_f32_e32 v193, v228
	v_exp_f32_e32 v194, v229
	v_exp_f32_e32 v183, v94
	v_exp_f32_e32 v184, v95
	v_exp_f32_e32 v188, v96
	v_exp_f32_e32 v190, v97
	v_exp_f32_e32 v185, v106
	v_exp_f32_e32 v186, v107
	s_add_i32 s53, s53, 2
	s_add_u32 s14, s14, 0x4000
	s_addc_u32 s15, s15, 0
	v_pk_fma_f32 v[160:161], v[82:83], s[50:51], v[230:231] op_sel_hi:[1,0,0]
	v_pk_fma_f32 v[158:159], v[84:85], s[50:51], v[230:231] op_sel_hi:[1,0,0]
	v_pk_fma_f32 v[82:83], v[86:87], s[50:51], v[230:231] op_sel_hi:[1,0,0]
	v_pk_fma_f32 v[156:157], v[88:89], s[50:51], v[230:231] op_sel_hi:[1,0,0]
	s_cmpk_gt_u32 s18, 0xfd
	v_fma_f32 v180, v182, v180, v240
	s_cbranch_scc1 .LBB0_578
	v_mov_b32_e32 v179, v198
	s_branch .LBB0_560
.Lmask_last:
	v_mov_b32_e32 v74, v163
	v_mov_b32_e32 v75, v163
	v_mov_b32_e32 v76, v163
	v_mov_b32_e32 v77, v163
	v_mov_b32_e32 v78, v163
	v_mov_b32_e32 v79, v163
	v_mov_b32_e32 v80, v163
	v_mov_b32_e32 v81, v163
	v_mov_b32_e32 v82, v163
	v_mov_b32_e32 v83, v163
	v_mov_b32_e32 v84, v163
	v_mov_b32_e32 v85, v163
	v_mov_b32_e32 v86, v163
	v_mov_b32_e32 v87, v163
	v_mov_b32_e32 v88, v163
	v_mov_b32_e32 v89, v163
	v_mov_b32_e32 v90, v163
	v_mov_b32_e32 v91, v163
	v_mov_b32_e32 v92, v163
	v_mov_b32_e32 v93, v163
	v_mov_b32_e32 v94, v163
	v_mov_b32_e32 v95, v163
	v_mov_b32_e32 v96, v163
	v_mov_b32_e32 v97, v163
	s_branch .Lmask_ret
.LBB0_578:
	ds_read_b128 v[128:131], v173 offset:36864
	ds_read_b128 v[132:135], v173 offset:37376
	ds_read_b128 v[120:123], v173 offset:38912
	ds_read_b128 v[124:127], v173 offset:39424
	ds_read_b128 v[92:95], v173 offset:40960
	ds_read_b128 v[96:99], v173 offset:41472
	ds_read_b128 v[84:87], v173 offset:43008
	ds_read_b128 v[88:91], v173 offset:43520
	v_exp_f32_e32 v64, v160
	v_exp_f32_e32 v67, v161
	v_exp_f32_e32 v70, v82
	v_exp_f32_e32 v71, v83
	v_exp_f32_e32 v74, v154
	v_exp_f32_e32 v75, v155
	v_exp_f32_e32 v78, v150
	v_exp_f32_e32 v79, v151
	v_mov_b32_e32 v100, v139
	v_mov_b32_e32 v104, v139
	v_mov_b32_e32 v101, v139
	v_mov_b32_e32 v105, v139
	v_mov_b32_e32 v102, v139
	v_mov_b32_e32 v106, v139
	v_mov_b32_e32 v103, v139
	v_mov_b32_e32 v107, v139
	v_exp_f32_e32 v68, v158
	v_exp_f32_e32 v69, v159
	v_exp_f32_e32 v72, v156
	v_exp_f32_e32 v73, v157
	v_exp_f32_e32 v76, v152
	v_exp_f32_e32 v77, v153
	v_exp_f32_e32 v80, v148
	v_exp_f32_e32 v81, v149
	v_cvt_pk_fp8_f32 v100, v65, v197
	v_cvt_pk_fp8_f32 v104, v64, v67
	v_cvt_pk_fp8_f32 v101, v195, v196
	v_cvt_pk_fp8_f32 v105, v70, v71
	v_cvt_pk_fp8_f32 v102, v193, v194
	v_cvt_pk_fp8_f32 v106, v74, v75
	v_cvt_pk_fp8_f32 v103, v188, v190
	v_cvt_pk_fp8_f32 v107, v78, v79
	v_cvt_pk_fp8_f32 v100, v187, v189 op_sel:[0,0,1]
	v_cvt_pk_fp8_f32 v104, v68, v69 op_sel:[0,0,1]
	v_cvt_pk_fp8_f32 v101, v191, v192 op_sel:[0,0,1]
	v_cvt_pk_fp8_f32 v105, v72, v73 op_sel:[0,0,1]
	v_cvt_pk_fp8_f32 v102, v183, v184 op_sel:[0,0,1]
	v_cvt_pk_fp8_f32 v106, v76, v77 op_sel:[0,0,1]
	v_cvt_pk_fp8_f32 v103, v185, v186 op_sel:[0,0,1]
	v_cvt_pk_fp8_f32 v107, v80, v81 op_sel:[0,0,1]
	s_and_saveexec_b64 s[4:5], s[6:7]
	s_cbranch_execz .LBB0_549
	v_mov_b32_e32 v113, v112
	v_mov_b32_e32 v114, v112
	v_mov_b32_e32 v115, v112
	v_mov_b32_e32 v116, v112
	v_mov_b32_e32 v117, v112
	v_mov_b32_e32 v118, v112
	v_mov_b32_e32 v119, v112
	s_nop 1
	v_mfma_scale_f32_32x32x64_f8f6f4 v[68:83], v[232:239], v[100:107], 0, v162, v162 op_sel_hi:[0,0,0]
	s_nop 15
	s_nop 3
	v_fmac_f32_e32 v68, v198, v180
	ds_write_b32 v178, v68
	s_branch .LBB0_549

; __global__ void __launch_bounds__(NTHREADS) mega(Params p, int ph_lo, int ph_hi) {
	.amdhsa_kernel _Z4mega6Paramsii
		.amdhsa_group_segment_fixed_size 0
		.amdhsa_private_segment_fixed_size 0
		.amdhsa_kernarg_size 424
		.amdhsa_user_sgpr_count 2
		.amdhsa_user_sgpr_dispatch_ptr 0
		.amdhsa_user_sgpr_queue_ptr 0
		.amdhsa_user_sgpr_kernarg_segment_ptr 1
		.amdhsa_user_sgpr_dispatch_id 0
		.amdhsa_user_sgpr_kernarg_preload_length 0
		.amdhsa_user_sgpr_kernarg_preload_offset 0
		.amdhsa_user_sgpr_private_segment_size 0
		.amdhsa_uses_dynamic_stack 0
		.amdhsa_enable_private_segment 0
		.amdhsa_system_sgpr_workgroup_id_x 1
		.amdhsa_system_sgpr_workgroup_id_y 0
		.amdhsa_system_sgpr_workgroup_id_z 0
		.amdhsa_system_sgpr_workgroup_info 0
		.amdhsa_system_vgpr_workitem_id 2
		.amdhsa_next_free_vgpr 256
		.amdhsa_next_free_sgpr 102
		.amdhsa_accum_offset 256
		.amdhsa_reserve_vcc 1
		.amdhsa_float_round_mode_32 0
		.amdhsa_float_round_mode_16_64 0
		.amdhsa_float_denorm_mode_32 3
		.amdhsa_float_denorm_mode_16_64 3
		.amdhsa_dx10_clamp 1
		.amdhsa_ieee_mode 1
		.amdhsa_fp16_overflow 0
		.amdhsa_tg_split 0
		.amdhsa_exception_fp_ieee_invalid_op 0
		.amdhsa_exception_fp_denorm_src 0
		.amdhsa_exception_fp_ieee_div_zero 0
		.amdhsa_exception_fp_ieee_overflow 0
		.amdhsa_exception_fp_ieee_underflow 0
		.amdhsa_exception_fp_ieee_inexact 0
		.amdhsa_exception_int_div_zero 0
	.end_amdhsa_kernel

; __global__ void __launch_bounds__(NTHREADS) mega(Params p, int ph_lo, int ph_hi) {
.Lfunc_end0:
	.size	_Z4mega6Paramsii, .Lfunc_end0-_Z4mega6Paramsii
	.set _Z4mega6Paramsii.num_vgpr, 256
	.set _Z4mega6Paramsii.num_agpr, 0
	.set _Z4mega6Paramsii.numbered_sgpr, 102
	.set _Z4mega6Paramsii.num_named_barrier, 0
	.set _Z4mega6Paramsii.private_seg_size, 0
	.set _Z4mega6Paramsii.uses_vcc, 1
	.set _Z4mega6Paramsii.uses_flat_scratch, 0
	.set _Z4mega6Paramsii.has_dyn_sized_stack, 0
	.set _Z4mega6Paramsii.has_recursion, 0
	.set _Z4mega6Paramsii.has_indirect_call, 0

; __global__ void __launch_bounds__(NTHREADS) mega(Params p, int ph_lo, int ph_hi) {
amdhsa.kernels:
  - .agpr_count:     0
    .args:
      - .offset:         0
        .size:           160
        .value_kind:     by_value
      - .offset:         160
        .size:           4
        .value_kind:     by_value
      - .offset:         164
        .size:           4
        .value_kind:     by_value
      - .offset:         168
        .size:           4
        .value_kind:     hidden_block_count_x
      - .offset:         172
        .size:           4
        .value_kind:     hidden_block_count_y
      - .offset:         176
        .size:           4
        .value_kind:     hidden_block_count_z
      - .offset:         180
        .size:           2
        .value_kind:     hidden_group_size_x
      - .offset:         182
        .size:           2
        .value_kind:     hidden_group_size_y
      - .offset:         184
        .size:           2
        .value_kind:     hidden_group_size_z
      - .offset:         186
        .size:           2
        .value_kind:     hidden_remainder_x
      - .offset:         188
        .size:           2
        .value_kind:     hidden_remainder_y
      - .offset:         190
        .size:           2
        .value_kind:     hidden_remainder_z
      - .offset:         208
        .size:           8
        .value_kind:     hidden_global_offset_x
      - .offset:         216
        .size:           8
        .value_kind:     hidden_global_offset_y
      - .offset:         224
        .size:           8
        .value_kind:     hidden_global_offset_z
      - .offset:         232
        .size:           2
        .value_kind:     hidden_grid_dims
      - .offset:         256
        .size:           8
        .value_kind:     hidden_multigrid_sync_arg
      - .offset:         288
        .size:           4
        .value_kind:     hidden_dynamic_lds_size
    .group_segment_fixed_size: 0
    .kernarg_segment_align: 8
    .kernarg_segment_size: 424
    .language:       OpenCL C
    .language_version:
      - 2
      - 0
    .max_flat_workgroup_size: 512
    .name:           _Z4mega6Paramsii
    .private_segment_fixed_size: 0
    .sgpr_count:     108
    .sgpr_spill_count: 15
    .symbol:         _Z4mega6Paramsii.kd
    .uniform_work_group_size: 1
    .uses_dynamic_stack: false
    .vgpr_count:     256
    .vgpr_spill_count: 0
    .wavefront_size: 64
